# attention: waves 0-3 delayed by s_sleep 2 after each per-tile barrier to de-phase the two waves of a SIMD
# speedup vs baseline: 1.0009x; 1.0009x over previous
; #define SBAR() __builtin_amdgcn_sched_barrier(0)
; #define SLOAD(i, k0) do { sr_[i].vs0 = ld8(&Vh[(long)((k0) + sr) * LDK + sc]); sr_[i].vs1 = ld8(&Vh[(long)((k0) + 32 + sr) * LDK + sc]); \
;     sr_[i].ks0 = ld8(&Kh[(long)((k0) + sr) * LDK + sc]); sr_[i].ks1 = ld8(&Kh[(long)((k0) + 32 + sr) * LDK + sc]); } while (0)
; DI void finishSM(f32x16& p0, f32x16& p1, float alpha, float& l_reg, bf16x8& pa0, bf16x8& pa1, bf16x8& pa2, bf16x8& pa3) {
;   for (int r = 0; r < 16; ++r) p1[r] = __builtin_amdgcn_exp2f(p1[r]);
;   float ps = 0; for (int r = 0; r < 16; ++r) ps += p0[r]; for (int r = 0; r < 16; ++r) ps += p1[r];
;   { auto rr = __builtin_amdgcn_permlane32_swap(__float_as_uint(ps), __float_as_uint(ps), false, false);
;     ps = __uint_as_float(rr[0]) + __uint_as_float(rr[1]); }
;   l_reg = l_reg * alpha + ps;
;     ...
;   PK4(p0, 0, pa0); PK4(p0, 8, pa1); PK4(p1, 0, pa2); PK4(p1, 8, pa3);
;     ...
; }
; DI void qkt(f32x16& p0, f32x16& p1, const bf16_t* Ks, const bf16x8* qr, int r32, int hi) {
;   p0 = f32x16{}; p1 = f32x16{};
;   for (int d0 = 0; d0 < 8; ++d0) { int cb = (d0 * 16 + hi * 8) * 2;
;     bf16x8 b0 = *reinterpret_cast<const bf16x8*>((const char*)Ks + KSWZ(r32, cb));
;     bf16x8 b1 = *reinterpret_cast<const bf16x8*>((const char*)Ks + KSWZ(32 + r32, cb));
;     p0 = __builtin_amdgcn_mfma_f32_32x32x16_bf16(b0, qr[d0], p0, 0, 0, 0);
;     p1 = __builtin_amdgcn_mfma_f32_32x32x16_bf16(b1, qr[d0], p1, 0, 0, 0); }
; DI void attn_dense_body(const bf16_t* __restrict__ Qb, const bf16_t* __restrict__ Kh, const bf16_t* __restrict__ Vh, ...
;     ...
;     SBAR(); qkt(pB0, pB1, (bf16_t*)((char*)K_lds + SHM_K), qr, r32, hi);
;     finishSM(pA0, pA1, alA, l_reg, pa0, pa1, pa2, pa3); SBAR();
;     SLOAD(SO, (j + 2) * KVBLK); SBAR();
;     pv_d0(o, vb0, pa0, pa1, pa2, pa3); partialSM(pB0, pB1, m_reg, mnB, alB);
.LBB0_835:
	ds_read_b128 v[64:67], v207 offset:49152
	ds_read_b128 v[68:71], v207 offset:57344
	ds_read_b128 v[232:235], v210 offset:49152
	ds_read_b128 v[236:239], v210 offset:57344
	v_add_f32_e32 v160, 0, v161
	v_add_f32_e32 v160, v175, v160
	s_waitcnt lgkmcnt(3)
	v_mfma_f32_32x32x16_bf16 v[80:95], v[64:67], v[116:119], 0
	v_add_f32_e32 v160, v162, v160
	v_add_f32_e32 v160, v219, v160
	v_add_f32_e32 v160, v174, v160
	v_add_f32_e32 v160, v222, v160
	v_add_f32_e32 v160, v163, v160
	v_add_f32_e32 v160, v173, v160
	v_add_f32_e32 v160, v164, v160
	s_waitcnt lgkmcnt(2)
	v_mfma_f32_32x32x16_bf16 v[64:79], v[68:71], v[116:119], 0
	ds_read_b128 v[240:243], v211 offset:49152
	ds_read_b128 v[244:247], v211 offset:57344
	v_add_f32_e32 v160, v171, v160
	v_add_f32_e32 v160, v165, v160
	v_add_f32_e32 v160, v172, v160
	v_exp_f32_e32 v158, v158
	v_add_f32_e32 v160, v166, v160
	v_exp_f32_e32 v159, v159
	v_add_f32_e32 v160, v169, v160
	s_waitcnt lgkmcnt(3)
	v_mfma_f32_32x32x16_bf16 v[80:95], v[232:235], v[124:127], v[80:95]
	v_exp_f32_e32 v156, v156
	v_add_f32_e32 v160, v167, v160
	v_exp_f32_e32 v157, v157
	v_add_f32_e32 v160, v170, v160
	v_exp_f32_e32 v152, v152
	v_add_f32_e32 v160, v158, v160
	v_exp_f32_e32 v153, v153
	s_waitcnt lgkmcnt(2)
	v_mfma_f32_32x32x16_bf16 v[64:79], v[236:239], v[124:127], v[64:79]
	ds_read_b128 v[232:235], v208 offset:49152
	ds_read_b128 v[236:239], v208 offset:57344
	v_add_f32_e32 v160, v159, v160
	v_exp_f32_e32 v148, v148
	v_add_f32_e32 v160, v156, v160
	v_exp_f32_e32 v149, v149
	v_add_f32_e32 v160, v157, v160
	v_exp_f32_e32 v146, v146
	s_waitcnt lgkmcnt(3)
	v_mfma_f32_32x32x16_bf16 v[80:95], v[240:243], v[120:123], v[80:95]
	v_add_f32_e32 v160, v152, v160
	v_exp_f32_e32 v147, v147
	v_add_f32_e32 v160, v153, v160
	v_exp_f32_e32 v154, v154
	v_add_f32_e32 v160, v148, v160
	v_exp_f32_e32 v155, v155
	v_add_f32_e32 v160, v149, v160
	s_waitcnt lgkmcnt(2)
	v_mfma_f32_32x32x16_bf16 v[64:79], v[244:247], v[120:123], v[64:79]
	ds_read_b128 v[240:243], v209 offset:49152
	ds_read_b128 v[244:247], v209 offset:57344
	v_exp_f32_e32 v150, v150
	v_add_f32_e32 v160, v146, v160
	v_exp_f32_e32 v151, v151
	v_add_f32_e32 v160, v147, v160
	v_exp_f32_e32 v144, v144
	v_add_f32_e32 v160, v154, v160
	s_waitcnt lgkmcnt(3)
	v_mfma_f32_32x32x16_bf16 v[80:95], v[232:235], v[112:115], v[80:95]
	v_exp_f32_e32 v145, v145
	v_add_f32_e32 v160, v155, v160
	v_add_f32_e32 v160, v150, v160
	v_add_f32_e32 v160, v151, v160
	v_add_f32_e32 v160, v144, v160
	v_add_f32_e32 v216, v145, v160
	v_mov_b32_e32 v217, v216
	s_waitcnt lgkmcnt(2)
	v_mfma_f32_32x32x16_bf16 v[64:79], v[236:239], v[112:115], v[64:79]
	ds_read_b128 v[232:235], v212 offset:49152
	ds_read_b128 v[236:239], v212 offset:57344
	v_permlane32_swap_b32_e32 v216, v217
	s_waitcnt lgkmcnt(3)
	v_mfma_f32_32x32x16_bf16 v[80:95], v[240:243], v[108:111], v[80:95]
	s_waitcnt lgkmcnt(2)
	v_mfma_f32_32x32x16_bf16 v[64:79], v[244:247], v[108:111], v[64:79]
	ds_read_b128 v[240:243], v213 offset:49152
	ds_read_b128 v[244:247], v213 offset:57344
	s_waitcnt lgkmcnt(3)
	v_mfma_f32_32x32x16_bf16 v[80:95], v[232:235], v[104:107], v[80:95]
	s_waitcnt lgkmcnt(2)
	v_mfma_f32_32x32x16_bf16 v[64:79], v[236:239], v[104:107], v[64:79]
	ds_read_b128 v[232:235], v214 offset:49152
	ds_read_b128 v[236:239], v214 offset:57344
	s_waitcnt lgkmcnt(3)
	v_mfma_f32_32x32x16_bf16 v[80:95], v[240:243], v[100:103], v[80:95]
	s_waitcnt lgkmcnt(2)
	v_mfma_f32_32x32x16_bf16 v[64:79], v[244:247], v[100:103], v[64:79]
	v_cvt_pk_bf16_f32 v160, v161, v175
	v_cvt_pk_bf16_f32 v161, v162, v219
	v_cvt_pk_bf16_f32 v162, v174, v222
	v_cvt_pk_bf16_f32 v163, v163, v173
	v_cvt_pk_bf16_f32 v164, v164, v171
	v_cvt_pk_bf16_f32 v165, v165, v172
	s_waitcnt lgkmcnt(1)
	v_mfma_f32_32x32x16_bf16 v[80:95], v[232:235], v[96:99], v[80:95]
	v_cvt_pk_bf16_f32 v166, v166, v169
	v_cvt_pk_bf16_f32 v167, v167, v170
	v_cvt_pk_bf16_f32 v170, v158, v159
	v_cvt_pk_bf16_f32 v171, v156, v157
	v_cvt_pk_bf16_f32 v172, v152, v153
	v_cvt_pk_bf16_f32 v173, v148, v149
	v_cvt_pk_bf16_f32 v218, v146, v147
	s_waitcnt lgkmcnt(0)
	v_mfma_f32_32x32x16_bf16 v[64:79], v[236:239], v[96:99], v[64:79]
	v_cvt_pk_bf16_f32 v219, v154, v155
	v_cvt_pk_bf16_f32 v220, v150, v151
	v_permlane32_swap_b32_e32 v160, v162
	v_cvt_pk_bf16_f32 v221, v144, v145
	v_permlane32_swap_b32_e32 v218, v220
	v_permlane32_swap_b32_e32 v161, v163
	v_permlane32_swap_b32_e32 v164, v166
	v_permlane32_swap_b32_e32 v165, v167
	v_permlane32_swap_b32_e32 v170, v172
	v_permlane32_swap_b32_e32 v171, v173
	v_permlane32_swap_b32_e32 v219, v221
	s_waitcnt vmcnt(0)
	ds_write_b128 v203, v[132:135] offset:32768
	ds_write_b128 v206, v[140:143] offset:32768
	s_mov_b32 s0, 0xffff4000
	v_add_co_u32_e32 v144, vcc, s0, v194
	s_movk_i32 s0, 0x8000
	s_nop 0
	v_addc_co_u32_e32 v145, vcc, -1, v195, vcc
	v_add_co_u32_e32 v148, vcc, s0, v194
	s_mov_b32 s0, 0xfeef4000
	s_nop 0
	v_addc_co_u32_e32 v149, vcc, -1, v195, vcc
	v_add_co_u32_e32 v152, vcc, s0, v194
	s_mov_b32 s0, 0xfeef8000
	s_nop 0
	v_addc_co_u32_e32 v153, vcc, -1, v195, vcc
	v_add_co_u32_e32 v156, vcc, s0, v194
	global_load_dwordx4 v[144:147], v[144:145], off
	s_nop 0
	global_load_dwordx4 v[148:151], v[148:149], off
	v_addc_co_u32_e32 v157, vcc, -1, v195, vcc
	global_load_dwordx4 v[152:155], v[152:153], off
	s_nop 0
	global_load_dwordx4 v[156:159], v[156:157], off
	ds_read_b64_tr_b16 v[232:233], v202 offset:0
	ds_read_b64_tr_b16 v[234:235], v202 offset:0x800
	ds_read_b64_tr_b16 v[236:237], v202 offset:0x1000
	ds_read_b64_tr_b16 v[238:239], v202 offset:0x1800
	ds_read_b64_tr_b16 v[240:241], v202 offset:0x2000
	ds_read_b64_tr_b16 v[242:243], v202 offset:0x2800
	ds_read_b64_tr_b16 v[244:245], v202 offset:0x3000
	ds_read_b64_tr_b16 v[246:247], v202 offset:0x3800
	s_waitcnt lgkmcnt(6)
; #define SWRITE(b, i) do { *(bf16x8*)((char*)V_lds + (b) * SHM_V + vst0) = sr_[i].vs0;          \
;     *(bf16x8*)((char*)V_lds + (b) * SHM_V + vst1) = sr_[i].vs1; int kc = sc * 2;               \
;     *(bf16x8*)((char*)K_lds + (b) * SHM_K + KSWZ(sr, kc)) = sr_[i].ks0;                       \
;     *(bf16x8*)((char*)K_lds + (b) * SHM_K + KSWZ(32 + sr, kc)) = sr_[i].ks1; } while (0)
; #define SWAIT() asm volatile("s_waitcnt vmcnt(4)" ::: "memory")
; #define RESC(a) do { if (__any((a) < 1.f)) { if (hi == 0) al_l[r32] = (a); asm volatile("s_waitcnt lgkmcnt(0)" ::: "memory"); \
;     for (int d = 0; d < 4; ++d) for (int r = 0; r < 16; ++r) o[d][r] *= al_l[crow(r, hi)]; } } while (0)
; DI void partialSM(f32x16& p0, f32x16& p1, float& m_reg, float& mn, float& alpha) {
;   constexpr float C = SCALE * 1.4426950408889634f;
;   float pmax = p0[0]; for (int r = 1; r < 16; ++r) pmax = fmaxf(pmax, p0[r]); for (int r = 0; r < 16; ++r) pmax = fmaxf(pmax, p1[r]);
;   { auto rr = __builtin_amdgcn_permlane32_swap(__float_as_uint(pmax), __float_as_uint(pmax), false, false);
;     pmax = fmaxf(__uint_as_float(rr[0]), __uint_as_float(rr[1])); }
;   if (__builtin_expect(__all(pmax - m_reg <= THR / SCALE), 1)) { mn = m_reg; alpha = 1.f; }
;   else { mn = fmaxf(m_reg, pmax); alpha = __builtin_amdgcn_exp2f((m_reg - mn) * C); m_reg = mn; }
; DI void attn_dense_body(const bf16_t* __restrict__ Qb, const bf16_t* __restrict__ Kh, const bf16_t* __restrict__ Vh, ...
;     ...
;     pv_d0(o, vb0, pa0, pa1, pa2, pa3); partialSM(pB0, pB1, m_reg, mnB, alB);
;     __syncthreads(); SWAIT(); SWRITE(0, SE);
;     RESC(alB); __syncthreads();
	s_nop 0
	v_mfma_f32_32x32x16_bf16 v[0:15], v[160:163], v[232:235], v[0:15]
	ds_read_b64_tr_b16 v[232:233], v202 offset:0x200
	ds_read_b64_tr_b16 v[234:235], v202 offset:0xa00
	s_waitcnt lgkmcnt(6)
	v_mfma_f32_32x32x16_bf16 v[0:15], v[164:167], v[236:239], v[0:15]
	ds_read_b64_tr_b16 v[236:237], v202 offset:0x1200
	ds_read_b64_tr_b16 v[238:239], v202 offset:0x1a00
	s_waitcnt lgkmcnt(6)
	v_mfma_f32_32x32x16_bf16 v[0:15], v[170:173], v[240:243], v[0:15]
	ds_read_b64_tr_b16 v[240:241], v202 offset:0x2200
	ds_read_b64_tr_b16 v[242:243], v202 offset:0x2a00
	s_waitcnt lgkmcnt(6)
	v_mfma_f32_32x32x16_bf16 v[0:15], v[218:221], v[244:247], v[0:15]
	ds_read_b64_tr_b16 v[244:245], v202 offset:0x3200
	ds_read_b64_tr_b16 v[246:247], v202 offset:0x3a00
	s_waitcnt lgkmcnt(6)
	v_mfma_f32_32x32x16_bf16 v[48:63], v[160:163], v[232:235], v[48:63]
	ds_read_b64_tr_b16 v[232:233], v202 offset:0x400
	ds_read_b64_tr_b16 v[234:235], v202 offset:0xc00
	s_waitcnt lgkmcnt(6)
	v_mfma_f32_32x32x16_bf16 v[48:63], v[164:167], v[236:239], v[48:63]
	ds_read_b64_tr_b16 v[236:237], v202 offset:0x1400
	ds_read_b64_tr_b16 v[238:239], v202 offset:0x1c00
	s_waitcnt lgkmcnt(6)
	v_mfma_f32_32x32x16_bf16 v[48:63], v[170:173], v[240:243], v[48:63]
	ds_read_b64_tr_b16 v[240:241], v202 offset:0x2400
	ds_read_b64_tr_b16 v[242:243], v202 offset:0x2c00
	s_waitcnt lgkmcnt(6)
	v_mfma_f32_32x32x16_bf16 v[48:63], v[218:221], v[244:247], v[48:63]
	ds_read_b64_tr_b16 v[244:245], v202 offset:0x3400
	ds_read_b64_tr_b16 v[246:247], v202 offset:0x3c00
	s_waitcnt lgkmcnt(6)
	v_mfma_f32_32x32x16_bf16 v[32:47], v[160:163], v[232:235], v[32:47]
	ds_read_b64_tr_b16 v[232:233], v202 offset:0x600
	ds_read_b64_tr_b16 v[234:235], v202 offset:0xe00
	s_waitcnt lgkmcnt(6)
	v_mfma_f32_32x32x16_bf16 v[32:47], v[164:167], v[236:239], v[32:47]
	ds_read_b64_tr_b16 v[236:237], v202 offset:0x1600
	ds_read_b64_tr_b16 v[238:239], v202 offset:0x1e00
	s_waitcnt lgkmcnt(6)
	v_mfma_f32_32x32x16_bf16 v[32:47], v[170:173], v[240:243], v[32:47]
	ds_read_b64_tr_b16 v[240:241], v202 offset:0x2600
	ds_read_b64_tr_b16 v[242:243], v202 offset:0x2e00
	s_waitcnt lgkmcnt(6)
	v_mfma_f32_32x32x16_bf16 v[32:47], v[218:221], v[244:247], v[32:47]
	ds_read_b64_tr_b16 v[244:245], v202 offset:0x3600
	ds_read_b64_tr_b16 v[246:247], v202 offset:0x3e00
	s_waitcnt lgkmcnt(6)
	v_mfma_f32_32x32x16_bf16 v[16:31], v[160:163], v[232:235], v[16:31]
	v_max_f32_e32 v160, v81, v81
	v_max_f32_e32 v161, v80, v80
	v_max_f32_e32 v160, v161, v160
	v_max3_f32 v160, v160, v82, v83
	v_max3_f32 v160, v160, v84, v85
	v_max3_f32 v160, v160, v86, v87
	v_max3_f32 v160, v160, v88, v89
	v_max3_f32 v160, v160, v90, v91
	v_max3_f32 v160, v160, v92, v93
	s_waitcnt lgkmcnt(4)
	v_mfma_f32_32x32x16_bf16 v[16:31], v[164:167], v[236:239], v[16:31]
	v_max3_f32 v160, v160, v94, v95
	v_max3_f32 v160, v160, v64, v65
	v_max3_f32 v160, v160, v66, v67
	v_max3_f32 v160, v160, v68, v69
	v_max3_f32 v160, v160, v70, v71
	v_max3_f32 v160, v160, v72, v73
	v_max3_f32 v160, v160, v74, v75
	v_max3_f32 v160, v160, v76, v77
	s_waitcnt lgkmcnt(2)
	v_mfma_f32_32x32x16_bf16 v[16:31], v[170:173], v[240:243], v[16:31]
	v_max3_f32 v160, v160, v78, v79
	v_mov_b32_e32 v161, v160
	s_nop 1
	v_permlane32_swap_b32_e32 v160, v161
	v_max_f32_e32 v161, v161, v161
	v_max_f32_e32 v160, v160, v160
	v_max_f32_e32 v160, v160, v161
	v_sub_f32_e32 v161, v160, v168
	v_cmp_ge_f32_e32 vcc, s95, v161
	v_max_f32_e32 v161, v168, v168
	v_max_f32_e32 v160, v161, v160
	s_waitcnt lgkmcnt(0)
	v_mfma_f32_32x32x16_bf16 v[16:31], v[218:221], v[244:247], v[16:31]
	v_sub_f32_e32 v161, v168, v160
	v_mul_f32_e32 v161, 0x3e0293ee, v161
	v_exp_f32_e32 v161, v161
	s_cmp_eq_u64 vcc, exec
	s_cselect_b64 s[0:1], -1, 0
	s_barrier
	s_cmp_ge_u32 s100, 4
	s_cbranch_scc1 .Lattn_nodelay0
	s_sleep 2
.Lattn_nodelay0:
	s_waitcnt vmcnt(4)
	v_cndmask_b32_e64 v218, v161, 1.0, s[0:1]
	v_cmp_gt_f32_e32 vcc, 1.0, v218
	s_waitcnt vmcnt(7)
	ds_write_b128 v204, v[128:131]
	s_waitcnt vmcnt(6)
	ds_write_b128 v205, v[136:139]
	s_cbranch_vccz .LBB0_839
	s_and_saveexec_b64 s[10:11], s[4:5]
	ds_write_b32 v199, v218 offset:128
	s_or_b64 exec, exec, s[10:11]
	s_waitcnt lgkmcnt(0)
	v_add_u32_e32 v161, v198, v180
	ds_read_b128 v[162:165], v161 offset:224
	ds_read_b128 v[170:173], v161 offset:192
	ds_read_b128 v[220:223], v161 offset:160
	ds_read_b128 v[232:235], v161 offset:128
	s_waitcnt lgkmcnt(3)
	v_pk_mul_f32 v[12:13], v[12:13], v[162:163]
	s_waitcnt lgkmcnt(2)
	v_pk_mul_f32 v[8:9], v[8:9], v[170:171]
	s_waitcnt lgkmcnt(1)
	v_pk_mul_f32 v[4:5], v[4:5], v[220:221]
	v_pk_mul_f32 v[14:15], v[14:15], v[164:165]
	v_pk_mul_f32 v[10:11], v[10:11], v[172:173]
	v_pk_mul_f32 v[6:7], v[6:7], v[222:223]
	s_waitcnt lgkmcnt(0)
	v_pk_mul_f32 v[2:3], v[2:3], v[234:235]
	v_pk_mul_f32 v[0:1], v[0:1], v[232:233]
	v_pk_mul_f32 v[60:61], v[60:61], v[162:163]
	v_pk_mul_f32 v[56:57], v[56:57], v[170:171]
	v_pk_mul_f32 v[52:53], v[52:53], v[220:221]
	v_pk_mul_f32 v[62:63], v[62:63], v[164:165]
	v_pk_mul_f32 v[58:59], v[58:59], v[172:173]
	v_pk_mul_f32 v[54:55], v[54:55], v[222:223]
	v_pk_mul_f32 v[50:51], v[50:51], v[234:235]
	v_pk_mul_f32 v[48:49], v[48:49], v[232:233]
	v_pk_mul_f32 v[44:45], v[44:45], v[162:163]
	v_pk_mul_f32 v[40:41], v[40:41], v[170:171]
	v_pk_mul_f32 v[36:37], v[36:37], v[220:221]
	v_pk_mul_f32 v[46:47], v[46:47], v[164:165]
	v_pk_mul_f32 v[42:43], v[42:43], v[172:173]
	v_pk_mul_f32 v[38:39], v[38:39], v[222:223]
	v_pk_mul_f32 v[34:35], v[34:35], v[234:235]
	v_pk_mul_f32 v[32:33], v[32:33], v[232:233]
	v_pk_mul_f32 v[28:29], v[28:29], v[162:163]
	v_pk_mul_f32 v[24:25], v[24:25], v[170:171]
	v_pk_mul_f32 v[20:21], v[20:21], v[220:221]
	v_pk_mul_f32 v[30:31], v[30:31], v[164:165]
	v_pk_mul_f32 v[26:27], v[26:27], v[172:173]
	v_pk_mul_f32 v[22:23], v[22:23], v[222:223]
	v_pk_mul_f32 v[18:19], v[18:19], v[234:235]
	v_pk_mul_f32 v[16:17], v[16:17], v[232:233]

; #define SWRITE(b, i) do { *(bf16x8*)((char*)V_lds + (b) * SHM_V + vst0) = sr_[i].vs0;          \
;     *(bf16x8*)((char*)V_lds + (b) * SHM_V + vst1) = sr_[i].vs1; int kc = sc * 2;               \
;     *(bf16x8*)((char*)K_lds + (b) * SHM_K + KSWZ(sr, kc)) = sr_[i].ks0;                       \
;     *(bf16x8*)((char*)K_lds + (b) * SHM_K + KSWZ(32 + sr, kc)) = sr_[i].ks1; } while (0)
; #define SWAIT() asm volatile("s_waitcnt vmcnt(4)" ::: "memory")
; #define RESC(a) do { if (__any((a) < 1.f)) { if (hi == 0) al_l[r32] = (a); asm volatile("s_waitcnt lgkmcnt(0)" ::: "memory"); \
;     for (int d = 0; d < 4; ++d) for (int r = 0; r < 16; ++r) o[d][r] *= al_l[crow(r, hi)]; } } while (0)
; DI void partialSM(f32x16& p0, f32x16& p1, float& m_reg, float& mn, float& alpha) {
;   constexpr float C = SCALE * 1.4426950408889634f;
;   float pmax = p0[0]; for (int r = 1; r < 16; ++r) pmax = fmaxf(pmax, p0[r]); for (int r = 0; r < 16; ++r) pmax = fmaxf(pmax, p1[r]);
;   { auto rr = __builtin_amdgcn_permlane32_swap(__float_as_uint(pmax), __float_as_uint(pmax), false, false);
;     pmax = fmaxf(__uint_as_float(rr[0]), __uint_as_float(rr[1])); }
;   if (__builtin_expect(__all(pmax - m_reg <= THR / SCALE), 1)) { mn = m_reg; alpha = 1.f; }
;   else { mn = fmaxf(m_reg, pmax); alpha = __builtin_amdgcn_exp2f((m_reg - mn) * C); m_reg = mn; }
; DI void attn_dense_body(const bf16_t* __restrict__ Qb, const bf16_t* __restrict__ Kh, const bf16_t* __restrict__ Vh, ...
;     ...
;     pv_d0(o, vb0 + (int)SHM_V, pa0, pa1, pa2, pa3); partialSM(pA0, pA1, m_reg, mnA, alA);
;     __syncthreads(); SWAIT(); SWRITE(1, SO);
;     RESC(alA); __syncthreads();
.LBB0_841:
	ds_read_b64_tr_b16 v[232:233], v201 offset:0
	ds_read_b64_tr_b16 v[234:235], v201 offset:0x800
	ds_read_b64_tr_b16 v[236:237], v201 offset:0x1000
	ds_read_b64_tr_b16 v[238:239], v201 offset:0x1800
	ds_read_b64_tr_b16 v[240:241], v201 offset:0x2000
	ds_read_b64_tr_b16 v[242:243], v201 offset:0x2800
	ds_read_b64_tr_b16 v[244:245], v201 offset:0x3000
	ds_read_b64_tr_b16 v[246:247], v201 offset:0x3800
	s_waitcnt lgkmcnt(6)
	s_nop 0
	v_mfma_f32_32x32x16_bf16 v[0:15], v[160:163], v[232:235], v[0:15]
	ds_read_b64_tr_b16 v[232:233], v201 offset:0x200
	ds_read_b64_tr_b16 v[234:235], v201 offset:0xa00
	s_waitcnt lgkmcnt(6)
	v_mfma_f32_32x32x16_bf16 v[0:15], v[164:167], v[236:239], v[0:15]
	ds_read_b64_tr_b16 v[236:237], v201 offset:0x1200
	ds_read_b64_tr_b16 v[238:239], v201 offset:0x1a00
	s_waitcnt lgkmcnt(6)
	v_mfma_f32_32x32x16_bf16 v[0:15], v[168:171], v[240:243], v[0:15]
	ds_read_b64_tr_b16 v[240:241], v201 offset:0x2200
	ds_read_b64_tr_b16 v[242:243], v201 offset:0x2a00
	s_waitcnt lgkmcnt(6)
	v_mfma_f32_32x32x16_bf16 v[0:15], v[172:175], v[244:247], v[0:15]
	ds_read_b64_tr_b16 v[244:245], v201 offset:0x3200
	ds_read_b64_tr_b16 v[246:247], v201 offset:0x3a00
	s_waitcnt lgkmcnt(6)
	v_mfma_f32_32x32x16_bf16 v[48:63], v[160:163], v[232:235], v[48:63]
	ds_read_b64_tr_b16 v[232:233], v201 offset:0x400
	ds_read_b64_tr_b16 v[234:235], v201 offset:0xc00
	s_waitcnt lgkmcnt(6)
	v_mfma_f32_32x32x16_bf16 v[48:63], v[164:167], v[236:239], v[48:63]
	ds_read_b64_tr_b16 v[236:237], v201 offset:0x1400
	ds_read_b64_tr_b16 v[238:239], v201 offset:0x1c00
	s_waitcnt lgkmcnt(6)
	v_mfma_f32_32x32x16_bf16 v[48:63], v[168:171], v[240:243], v[48:63]
	ds_read_b64_tr_b16 v[240:241], v201 offset:0x2400
	ds_read_b64_tr_b16 v[242:243], v201 offset:0x2c00
	s_waitcnt lgkmcnt(6)
	v_mfma_f32_32x32x16_bf16 v[48:63], v[172:175], v[244:247], v[48:63]
	ds_read_b64_tr_b16 v[244:245], v201 offset:0x3400
	ds_read_b64_tr_b16 v[246:247], v201 offset:0x3c00
	s_waitcnt lgkmcnt(6)
	v_mfma_f32_32x32x16_bf16 v[32:47], v[160:163], v[232:235], v[32:47]
	ds_read_b64_tr_b16 v[232:233], v201 offset:0x600
	ds_read_b64_tr_b16 v[234:235], v201 offset:0xe00
	s_waitcnt lgkmcnt(6)
	v_mfma_f32_32x32x16_bf16 v[32:47], v[164:167], v[236:239], v[32:47]
	ds_read_b64_tr_b16 v[236:237], v201 offset:0x1600
	ds_read_b64_tr_b16 v[238:239], v201 offset:0x1e00
	s_waitcnt lgkmcnt(6)
	v_mfma_f32_32x32x16_bf16 v[32:47], v[168:171], v[240:243], v[32:47]
	ds_read_b64_tr_b16 v[240:241], v201 offset:0x2600
	ds_read_b64_tr_b16 v[242:243], v201 offset:0x2e00
	s_waitcnt lgkmcnt(6)
	v_mfma_f32_32x32x16_bf16 v[32:47], v[172:175], v[244:247], v[32:47]
	ds_read_b64_tr_b16 v[244:245], v201 offset:0x3600
	ds_read_b64_tr_b16 v[246:247], v201 offset:0x3e00
	s_waitcnt lgkmcnt(6)
	v_mfma_f32_32x32x16_bf16 v[16:31], v[160:163], v[232:235], v[16:31]
	v_max_f32_e32 v160, v81, v81
	v_max_f32_e32 v161, v80, v80
	v_max_f32_e32 v160, v161, v160
	v_max3_f32 v160, v160, v82, v83
	v_max3_f32 v160, v160, v84, v85
	v_max3_f32 v160, v160, v86, v87
	v_max3_f32 v160, v160, v88, v89
	v_max3_f32 v160, v160, v90, v91
	v_max3_f32 v160, v160, v92, v93
	s_waitcnt lgkmcnt(4)
	v_mfma_f32_32x32x16_bf16 v[16:31], v[164:167], v[236:239], v[16:31]
	v_max3_f32 v160, v160, v94, v95
	v_max3_f32 v160, v160, v64, v65
	v_max3_f32 v160, v160, v66, v67
	v_max3_f32 v160, v160, v68, v69
	v_max3_f32 v160, v160, v70, v71
	v_max3_f32 v160, v160, v72, v73
	v_max3_f32 v160, v160, v74, v75
	v_max3_f32 v160, v160, v76, v77
	s_waitcnt lgkmcnt(2)
	v_mfma_f32_32x32x16_bf16 v[16:31], v[168:171], v[240:243], v[16:31]
	v_max3_f32 v160, v160, v78, v79
	v_mov_b32_e32 v161, v160
	s_nop 1
	v_permlane32_swap_b32_e32 v160, v161
	v_max_f32_e32 v161, v161, v161
	v_max_f32_e32 v160, v160, v160
	v_max_f32_e32 v160, v160, v161
	v_sub_f32_e32 v161, v160, v219
	v_cmp_ge_f32_e32 vcc, s95, v161
	v_max_f32_e32 v161, v219, v219
	v_max_f32_e32 v161, v161, v160
	s_waitcnt lgkmcnt(0)
	v_mfma_f32_32x32x16_bf16 v[16:31], v[172:175], v[244:247], v[16:31]
	v_sub_f32_e32 v160, v219, v161
	v_mul_f32_e32 v160, 0x3e0293ee, v160
	v_exp_f32_e32 v160, v160
	s_cmp_eq_u64 vcc, exec
	s_cselect_b64 s[0:1], -1, 0
	s_barrier
	s_cmp_ge_u32 s100, 4
	s_cbranch_scc1 .Lattn_nodelay1
	s_sleep 2
.Lattn_nodelay1:
	s_waitcnt vmcnt(4)
	v_cndmask_b32_e64 v160, v160, 1.0, s[0:1]
	v_cmp_gt_f32_e32 vcc, 1.0, v160
	ds_write_b128 v204, v[144:147] offset:16384
	ds_write_b128 v205, v[148:151] offset:16384
	s_cbranch_vccz .LBB0_845
	s_and_saveexec_b64 s[12:13], s[4:5]
	ds_write_b32 v199, v160 offset:128
	s_or_b64 exec, exec, s[12:13]
	s_waitcnt lgkmcnt(0)
	v_add_u32_e32 v156, v198, v180
	ds_read_b128 v[144:147], v156 offset:224
	ds_read_b128 v[148:151], v156 offset:192
	ds_read_b128 v[152:155], v156 offset:160
	ds_read_b128 v[156:159], v156 offset:128
	s_waitcnt lgkmcnt(3)
	v_pk_mul_f32 v[12:13], v[12:13], v[144:145]
	s_waitcnt lgkmcnt(2)
	v_pk_mul_f32 v[8:9], v[8:9], v[148:149]
	s_waitcnt lgkmcnt(1)
	v_pk_mul_f32 v[4:5], v[4:5], v[152:153]
	v_pk_mul_f32 v[14:15], v[14:15], v[146:147]
	v_pk_mul_f32 v[10:11], v[10:11], v[150:151]
	v_pk_mul_f32 v[6:7], v[6:7], v[154:155]
	s_waitcnt lgkmcnt(0)
	v_pk_mul_f32 v[2:3], v[2:3], v[158:159]
	v_pk_mul_f32 v[0:1], v[0:1], v[156:157]
	v_pk_mul_f32 v[60:61], v[60:61], v[144:145]
	v_pk_mul_f32 v[56:57], v[56:57], v[148:149]
	v_pk_mul_f32 v[52:53], v[52:53], v[152:153]
	v_pk_mul_f32 v[62:63], v[62:63], v[146:147]
	v_pk_mul_f32 v[58:59], v[58:59], v[150:151]
	v_pk_mul_f32 v[54:55], v[54:55], v[154:155]
	v_pk_mul_f32 v[50:51], v[50:51], v[158:159]
	v_pk_mul_f32 v[48:49], v[48:49], v[156:157]
	v_pk_mul_f32 v[44:45], v[44:45], v[144:145]
	v_pk_mul_f32 v[40:41], v[40:41], v[148:149]
	v_pk_mul_f32 v[36:37], v[36:37], v[152:153]
	v_pk_mul_f32 v[46:47], v[46:47], v[146:147]
	v_pk_mul_f32 v[42:43], v[42:43], v[150:151]
	v_pk_mul_f32 v[38:39], v[38:39], v[154:155]
	v_pk_mul_f32 v[34:35], v[34:35], v[158:159]
	v_pk_mul_f32 v[32:33], v[32:33], v[156:157]
	v_pk_mul_f32 v[28:29], v[28:29], v[144:145]
	v_pk_mul_f32 v[24:25], v[24:25], v[148:149]
	v_pk_mul_f32 v[20:21], v[20:21], v[152:153]
	v_pk_mul_f32 v[30:31], v[30:31], v[146:147]
	v_pk_mul_f32 v[26:27], v[26:27], v[150:151]
	v_pk_mul_f32 v[22:23], v[22:23], v[154:155]
	v_pk_mul_f32 v[18:19], v[18:19], v[158:159]
	v_pk_mul_f32 v[16:17], v[16:17], v[156:157]
